# P3c: LDS operand reads skipped in the phases whose MFMAs are skipped (block-diagonal w_uk), on top of final
# baseline (speedup 1.0000x reference)
; #define G8_STAGE(bufoff, gbase, NM) do { _Pragma("unroll") for (int _i = 0; _i < 2; ++_i) { \
;     const char* _b = (const char*)(gbase) + (_i ? p2##NM : (size_t)0); asm volatile("" : "+s"(_b));     \
;     __builtin_amdgcn_global_load_lds((const unsigned*)(_b + voff##NM), (LAS unsigned*)(lds + (bufoff) + ldsw + _i * 8192), 16, 0, 0); } } while (0)
; #define G8_WAIT_V(n) asm volatile("s_waitcnt vmcnt(" #n ")" ::: "memory")
; #define G8_WAIT_L(n) asm volatile("s_waitcnt lgkmcnt(" #n ")" ::: "memory")
; #define G8_BAR __builtin_amdgcn_s_barrier()
; #define G8_SCHED __builtin_amdgcn_sched_barrier(0)
;     ...
;       G8_LDB(B0, 0, 0); G8_LDB(B1, 0, 1); G8_SCHED; G8_LDA(At, 0, 0); G8_STAGE(G8_SA(1, 1), a1, A);
;       const bool d0a = (BD == 0) || (BD == 1 && t < (nt >> 1)) || (BD == 2 && !(cur.pn & 1));
;       const bool d1a = (BD == 0) || (BD == 1 && t >= (nt >> 1)) || (BD == 2 && !(cur.pn & 1));
;       const bool d0b = (BD == 0) || (BD == 1 && t < (nt >> 1)) || (BD == 2 && (cur.pn & 1));
;       const bool d1b = (BD == 0) || (BD == 1 && t >= (nt >> 1)) || (BD == 2 && (cur.pn & 1));
;       G8_WAIT_V(8); G8_WAIT_L(0); G8_BAR; if (d0a) G8_MMA(0, 0, At, B0); if (d1a) G8_MMA(0, 1, At, B1); G8_BAR; G8_SCHED;
;       G8_LDA(At, 0, 1); G8_STAGE(G8_SB(0, 0), b2, B); G8_STAGE(G8_SB(0, 1), b2 + hstepB, B); G8_STAGE(G8_SA(0, 0), a2, A);
;       G8_WAIT_V(8); G8_WAIT_L(0); G8_BAR; if (d0a) G8_MMA(1, 0, At, B0); if (d1a) G8_MMA(1, 1, At, B1); G8_BAR; G8_SCHED;
.LBB0_961:
	s_add_u32 s60, s8, 0x80080
	s_addc_u32 s61, s9, 0
	s_add_u32 s36, s28, 0x80
	s_addc_u32 s37, s29, 0
	s_add_u32 s38, s4, 0x80
	s_addc_u32 s39, s5, 0
	s_mov_b64 s[42:43], s[4:5]
	s_mov_b64 s[8:9], s[28:29]
	s_and_b32 s27, s34, 1
	s_cmp_eq_u32 s27, 1
	s_cbranch_scc1 .Lq3_r1a
	ds_read_b128 v[0:3], v202
	ds_read_b128 v[4:7], v202 offset:1024
	ds_read_b128 v[8:11], v202 offset:2048
	ds_read_b128 v[12:15], v202 offset:3072
	ds_read_b128 v[16:19], v203
	ds_read_b128 v[20:23], v203 offset:1024
	ds_read_b128 v[24:27], v203 offset:2048
	ds_read_b128 v[28:31], v203 offset:3072
.Lq3_r1a:
	s_and_b32 s27, s34, 1
	s_cmp_eq_u32 s27, 0
	s_cselect_b64 s[44:45], -1, 0
	s_cmp_eq_u32 s27, 1
	s_cselect_b64 s[40:41], -1, 0
	s_and_b64 vcc, exec, s[40:41]
	s_add_i32 m0, s0, 0xc000
	s_mov_b64 s[62:63], s[60:61]
	s_add_u32 s60, s60, 0x40000
	s_waitcnt lgkmcnt(0)
	s_cbranch_vccnz .Lq3_r1b
	ds_read_b128 v[32:35], v204
	ds_read_b128 v[36:39], v204 offset:1024
	ds_read_b128 v[40:43], v204 offset:2048
	ds_read_b128 v[44:47], v204 offset:3072
	ds_read_b128 v[48:51], v204 offset:4096
	ds_read_b128 v[52:55], v204 offset:5120
	ds_read_b128 v[56:59], v204 offset:6144
	ds_read_b128 v[60:63], v204 offset:7168
.Lq3_r1b:
	s_addc_u32 s61, s61, 0
	v_lshl_add_u64 v[66:67], s[62:63], 0, v[196:197]
	global_load_lds_dwordx4 v[66:67], off
	s_add_i32 m0, s0, 0xe000
	v_lshl_add_u64 v[66:67], s[60:61], 0, v[196:197]
	global_load_lds_dwordx4 v[66:67], off
	s_waitcnt vmcnt(8)
	s_waitcnt lgkmcnt(0)
	v_mov_b32_e32 v66, v65
	v_mov_b32_e32 v67, v65
	v_mov_b32_e32 v64, v65
	v_mov_b64_e32 v[86:87], v[66:67]
	v_mov_b64_e32 v[90:91], v[66:67]
	v_mov_b64_e32 v[118:119], v[66:67]
	v_mov_b64_e32 v[122:123], v[66:67]
	v_mov_b64_e32 v[150:151], v[66:67]
	v_mov_b64_e32 v[154:155], v[66:67]
	v_mov_b64_e32 v[182:183], v[66:67]
	v_mov_b64_e32 v[186:187], v[66:67]
	v_mov_b64_e32 v[94:95], v[66:67]
	v_mov_b64_e32 v[98:99], v[66:67]
	v_mov_b64_e32 v[126:127], v[66:67]
	v_mov_b64_e32 v[130:131], v[66:67]
	v_mov_b64_e32 v[158:159], v[66:67]
	v_mov_b64_e32 v[162:163], v[66:67]
	v_mov_b64_e32 v[190:191], v[66:67]
	v_mov_b64_e32 v[194:195], v[66:67]
	s_and_b64 vcc, exec, s[40:41]
	v_mov_b64_e32 v[84:85], v[64:65]
	v_mov_b64_e32 v[88:89], v[64:65]
	v_mov_b64_e32 v[116:117], v[64:65]
	v_mov_b64_e32 v[120:121], v[64:65]
	v_mov_b64_e32 v[148:149], v[64:65]
	v_mov_b64_e32 v[152:153], v[64:65]
	v_mov_b64_e32 v[180:181], v[64:65]
	v_mov_b64_e32 v[184:185], v[64:65]
	v_mov_b64_e32 v[92:93], v[64:65]
	v_mov_b64_e32 v[96:97], v[64:65]
	v_mov_b64_e32 v[124:125], v[64:65]
	v_mov_b64_e32 v[128:129], v[64:65]
	v_mov_b64_e32 v[156:157], v[64:65]
	v_mov_b64_e32 v[160:161], v[64:65]
	v_mov_b64_e32 v[188:189], v[64:65]
	v_mov_b64_e32 v[192:193], v[64:65]
	s_barrier
	s_cbranch_vccnz .LBB0_963
	s_setprio 1
	s_waitcnt lgkmcnt(0)
	v_mfma_f32_16x16x128_f8f6f4 v[192:195], v[0:7], v[32:39], 0
	v_mfma_f32_16x16x128_f8f6f4 v[188:191], v[8:15], v[32:39], 0
	v_mfma_f32_16x16x128_f8f6f4 v[160:163], v[0:7], v[40:47], 0
	v_mfma_f32_16x16x128_f8f6f4 v[156:159], v[8:15], v[40:47], 0
	v_mfma_f32_16x16x128_f8f6f4 v[128:131], v[0:7], v[48:55], 0
	v_mfma_f32_16x16x128_f8f6f4 v[124:127], v[8:15], v[48:55], 0
	v_mfma_f32_16x16x128_f8f6f4 v[96:99], v[0:7], v[56:63], 0
	v_mfma_f32_16x16x128_f8f6f4 v[92:95], v[8:15], v[56:63], 0
	s_setprio 0
	s_setprio 1
	v_mfma_f32_16x16x128_f8f6f4 v[184:187], v[16:23], v[32:39], 0
	v_mfma_f32_16x16x128_f8f6f4 v[180:183], v[24:31], v[32:39], 0
	v_mfma_f32_16x16x128_f8f6f4 v[152:155], v[16:23], v[40:47], 0
	v_mfma_f32_16x16x128_f8f6f4 v[148:151], v[24:31], v[40:47], 0
	v_mfma_f32_16x16x128_f8f6f4 v[120:123], v[16:23], v[48:55], 0
	v_mfma_f32_16x16x128_f8f6f4 v[116:119], v[24:31], v[48:55], 0
	v_mfma_f32_16x16x128_f8f6f4 v[88:91], v[16:23], v[56:63], 0
	v_mfma_f32_16x16x128_f8f6f4 v[84:87], v[24:31], v[56:63], 0
	s_setprio 0
.LBB0_963:
	s_barrier
	s_mov_b64 s[60:61], s[42:43]
	s_waitcnt lgkmcnt(0)
	s_cbranch_vccnz .Lq3_r2
	ds_read_b128 v[32:35], v204 offset:16384
	ds_read_b128 v[36:39], v204 offset:17408
	ds_read_b128 v[40:43], v204 offset:18432
	ds_read_b128 v[44:47], v204 offset:19456
	ds_read_b128 v[48:51], v204 offset:20480
	ds_read_b128 v[52:55], v204 offset:21504
	ds_read_b128 v[56:59], v204 offset:22528
	ds_read_b128 v[60:63], v204 offset:23552
.Lq3_r2:
	s_mov_b32 m0, s1
	v_lshl_add_u64 v[66:67], s[60:61], 0, v[198:199]
	s_add_u32 s60, s42, 0x4000
	s_addc_u32 s61, s43, 0
	global_load_lds_dwordx4 v[66:67], off
	s_mov_b32 m0, s2
	v_lshl_add_u64 v[66:67], s[60:61], 0, v[198:199]
	s_add_u32 s60, s42, 0x8000
	s_addc_u32 s61, s43, 0
	s_add_u32 s42, s42, 0xc000
	global_load_lds_dwordx4 v[66:67], off
	s_mov_b32 m0, s3
	v_lshl_add_u64 v[66:67], s[60:61], 0, v[198:199]
	s_addc_u32 s43, s43, 0
	global_load_lds_dwordx4 v[66:67], off
	s_mov_b32 m0, s15
	v_lshl_add_u64 v[66:67], s[42:43], 0, v[198:199]
	s_mov_b64 s[42:43], s[8:9]
	global_load_lds_dwordx4 v[66:67], off
	s_mov_b32 m0, s0
	v_lshl_add_u64 v[66:67], s[42:43], 0, v[196:197]
	s_add_u32 s42, s8, 0x40000
	s_addc_u32 s43, s9, 0
	global_load_lds_dwordx4 v[66:67], off
	s_mov_b32 m0, s31
	v_lshl_add_u64 v[66:67], s[42:43], 0, v[196:197]
	global_load_lds_dwordx4 v[66:67], off
	s_waitcnt vmcnt(8)
	s_waitcnt lgkmcnt(0)
	s_andn2_b64 vcc, exec, s[44:45]
	s_barrier
	s_cbranch_vccnz .LBB0_965
	s_setprio 1
	s_waitcnt lgkmcnt(0)
	v_mfma_f32_16x16x128_f8f6f4 v[176:179], v[0:7], v[32:39], 0
	v_mfma_f32_16x16x128_f8f6f4 v[172:175], v[8:15], v[32:39], 0
	v_mfma_f32_16x16x128_f8f6f4 v[144:147], v[0:7], v[40:47], 0
	v_mfma_f32_16x16x128_f8f6f4 v[140:143], v[8:15], v[40:47], 0
	v_mfma_f32_16x16x128_f8f6f4 v[112:115], v[0:7], v[48:55], 0
	v_mfma_f32_16x16x128_f8f6f4 v[108:111], v[8:15], v[48:55], 0
	v_mfma_f32_16x16x128_f8f6f4 v[80:83], v[0:7], v[56:63], 0
	v_mfma_f32_16x16x128_f8f6f4 v[76:79], v[8:15], v[56:63], 0
	s_setprio 0
	s_setprio 1
	v_mfma_f32_16x16x128_f8f6f4 v[168:171], v[16:23], v[32:39], 0
	v_mfma_f32_16x16x128_f8f6f4 v[164:167], v[24:31], v[32:39], 0
	v_mfma_f32_16x16x128_f8f6f4 v[136:139], v[16:23], v[40:47], 0
	v_mfma_f32_16x16x128_f8f6f4 v[132:135], v[24:31], v[40:47], 0
	v_mfma_f32_16x16x128_f8f6f4 v[104:107], v[16:23], v[48:55], 0
	v_mfma_f32_16x16x128_f8f6f4 v[100:103], v[24:31], v[48:55], 0
	v_mfma_f32_16x16x128_f8f6f4 v[72:75], v[16:23], v[56:63], 0
	v_mfma_f32_16x16x128_f8f6f4 v[68:71], v[24:31], v[56:63], 0
	s_setprio 0
	s_branch .LBB0_966

; #define G8_STAGE(bufoff, gbase, NM) do { _Pragma("unroll") for (int _i = 0; _i < 2; ++_i) { \
;     const char* _b = (const char*)(gbase) + (_i ? p2##NM : (size_t)0); asm volatile("" : "+s"(_b));     \
;     __builtin_amdgcn_global_load_lds((const unsigned*)(_b + voff##NM), (LAS unsigned*)(lds + (bufoff) + ldsw + _i * 8192), 16, 0, 0); } } while (0)
; #define G8_WAIT_V(n) asm volatile("s_waitcnt vmcnt(" #n ")" ::: "memory")
; #define G8_WAIT_L(n) asm volatile("s_waitcnt lgkmcnt(" #n ")" ::: "memory")
; #define G8_BAR __builtin_amdgcn_s_barrier()
; #define G8_SCHED __builtin_amdgcn_sched_barrier(0)
;     ...
;       G8_LDB(B0, 1, 0); G8_LDB(B1, 1, 1); G8_SCHED; G8_LDA(At, 1, 0); G8_STAGE(G8_SA(0, 1), a2 + hstepA, A);
;       G8_WAIT_V(8); G8_WAIT_L(0); G8_BAR; if (d0b) G8_MMA(0, 0, At, B0); if (d1b) G8_MMA(0, 1, At, B1); G8_BAR; G8_SCHED;
;       G8_LDA(At, 1, 1); G8_STAGE(G8_SB(1, 0), b3, B); G8_STAGE(G8_SB(1, 1), b3 + hstepB, B); G8_STAGE(G8_SA(1, 0), a3, A);
;       G8_WAIT_V(8); G8_WAIT_L(0); G8_BAR; if (d0b) G8_MMA(1, 0, At, B0); if (d1b) G8_MMA(1, 1, At, B1); G8_BAR; G8_SCHED;
.LBB0_966:
	s_barrier
	s_cbranch_vccz .Lq3_r3a
	v_add_u32_e32 v12, 0x18000, v201
	v_add_u32_e32 v28, 0x1000, v12
	ds_read_b128 v[0:3], v12
	ds_read_b128 v[4:7], v12 offset:1024
	ds_read_b128 v[8:11], v12 offset:2048
	ds_read_b128 v[12:15], v12 offset:3072
	ds_read_b128 v[16:19], v28
	ds_read_b128 v[20:23], v28 offset:1024
	ds_read_b128 v[24:27], v28 offset:2048
	ds_read_b128 v[28:31], v28 offset:3072
.Lq3_r3a:
	s_add_u32 s42, s8, 0x80000
	s_addc_u32 s43, s9, 0
	s_add_u32 s8, s8, 0xc0000
	s_mov_b32 m0, s33
	s_waitcnt lgkmcnt(0)
	s_cbranch_vccz .Lq3_r3b
	ds_read_b128 v[32:35], v204 offset:32768
	ds_read_b128 v[36:39], v204 offset:33792
	ds_read_b128 v[40:43], v204 offset:34816
	ds_read_b128 v[44:47], v204 offset:35840
	ds_read_b128 v[48:51], v204 offset:36864
	ds_read_b128 v[52:55], v204 offset:37888
	ds_read_b128 v[56:59], v204 offset:38912
	ds_read_b128 v[60:63], v204 offset:39936
.Lq3_r3b:
	s_addc_u32 s9, s9, 0
	v_lshl_add_u64 v[66:67], s[42:43], 0, v[196:197]
	global_load_lds_dwordx4 v[66:67], off
	s_mov_b32 m0, s46
	v_lshl_add_u64 v[66:67], s[8:9], 0, v[196:197]
	global_load_lds_dwordx4 v[66:67], off
	s_waitcnt vmcnt(8)
	s_waitcnt lgkmcnt(0)
	v_cndmask_b32_e64 v64, 0, 1, s[40:41]
	v_cmp_ne_u32_e64 s[8:9], 1, v64
	s_andn2_b64 vcc, exec, s[40:41]
	s_barrier
	s_cbranch_vccnz .LBB0_968
	s_setprio 1
	s_waitcnt lgkmcnt(0)
	v_mfma_f32_16x16x128_f8f6f4 v[192:195], v[0:7], v[32:39], v[192:195]
	v_mfma_f32_16x16x128_f8f6f4 v[188:191], v[8:15], v[32:39], v[188:191]
	v_mfma_f32_16x16x128_f8f6f4 v[160:163], v[0:7], v[40:47], v[160:163]
	v_mfma_f32_16x16x128_f8f6f4 v[156:159], v[8:15], v[40:47], v[156:159]
	v_mfma_f32_16x16x128_f8f6f4 v[128:131], v[0:7], v[48:55], v[128:131]
	v_mfma_f32_16x16x128_f8f6f4 v[124:127], v[8:15], v[48:55], v[124:127]
	v_mfma_f32_16x16x128_f8f6f4 v[96:99], v[0:7], v[56:63], v[96:99]
	v_mfma_f32_16x16x128_f8f6f4 v[92:95], v[8:15], v[56:63], v[92:95]
	s_setprio 0
	s_setprio 1
	v_mfma_f32_16x16x128_f8f6f4 v[184:187], v[16:23], v[32:39], v[184:187]
	v_mfma_f32_16x16x128_f8f6f4 v[180:183], v[24:31], v[32:39], v[180:183]
	v_mfma_f32_16x16x128_f8f6f4 v[152:155], v[16:23], v[40:47], v[152:155]
	v_mfma_f32_16x16x128_f8f6f4 v[148:151], v[24:31], v[40:47], v[148:151]
	v_mfma_f32_16x16x128_f8f6f4 v[120:123], v[16:23], v[48:55], v[120:123]
	v_mfma_f32_16x16x128_f8f6f4 v[116:119], v[24:31], v[48:55], v[116:119]
	v_mfma_f32_16x16x128_f8f6f4 v[88:91], v[16:23], v[56:63], v[88:91]
	v_mfma_f32_16x16x128_f8f6f4 v[84:87], v[24:31], v[56:63], v[84:87]
	s_setprio 0
.LBB0_968:
	s_barrier
	s_mov_b64 s[40:41], s[38:39]
	s_waitcnt lgkmcnt(0)
	s_cbranch_vccnz .Lq3_r4
	ds_read_b128 v[32:35], v204 offset:49152
	ds_read_b128 v[36:39], v204 offset:50176
	ds_read_b128 v[40:43], v204 offset:51200
	ds_read_b128 v[44:47], v204 offset:52224
	ds_read_b128 v[48:51], v204 offset:53248
	ds_read_b128 v[52:55], v204 offset:54272
	ds_read_b128 v[56:59], v204 offset:55296
	ds_read_b128 v[60:63], v204 offset:56320
.Lq3_r4:
	s_mov_b32 m0, s47
	v_lshl_add_u64 v[66:67], s[40:41], 0, v[198:199]
	s_add_u32 s40, s38, 0x4000
	s_addc_u32 s41, s39, 0
	global_load_lds_dwordx4 v[66:67], off
	s_mov_b32 m0, s48
	v_lshl_add_u64 v[66:67], s[40:41], 0, v[198:199]
	s_add_u32 s40, s38, 0x8000
	s_addc_u32 s41, s39, 0
	s_add_u32 s38, s38, 0xc000
	global_load_lds_dwordx4 v[66:67], off
	s_mov_b32 m0, s51
	v_lshl_add_u64 v[66:67], s[40:41], 0, v[198:199]
	s_addc_u32 s39, s39, 0
	global_load_lds_dwordx4 v[66:67], off
	s_mov_b32 m0, s52
	v_lshl_add_u64 v[66:67], s[38:39], 0, v[198:199]
	s_mov_b64 s[38:39], s[36:37]
	s_add_u32 s36, s36, 0x40000
	global_load_lds_dwordx4 v[66:67], off
	s_mov_b32 m0, s49
	v_lshl_add_u64 v[66:67], s[38:39], 0, v[196:197]
	s_addc_u32 s37, s37, 0
	global_load_lds_dwordx4 v[66:67], off
	s_mov_b32 m0, s50
	v_lshl_add_u64 v[66:67], s[36:37], 0, v[196:197]
	global_load_lds_dwordx4 v[66:67], off
	s_waitcnt vmcnt(8)
	s_waitcnt lgkmcnt(0)
	s_and_b64 vcc, exec, s[8:9]
	s_barrier
	s_cbranch_vccnz .LBB0_970
	s_setprio 1
	s_waitcnt lgkmcnt(0)
	v_mfma_f32_16x16x128_f8f6f4 v[176:179], v[0:7], v[32:39], v[176:179]
	v_mfma_f32_16x16x128_f8f6f4 v[172:175], v[8:15], v[32:39], v[172:175]
	v_mfma_f32_16x16x128_f8f6f4 v[144:147], v[0:7], v[40:47], v[144:147]
	v_mfma_f32_16x16x128_f8f6f4 v[140:143], v[8:15], v[40:47], v[140:143]
	v_mfma_f32_16x16x128_f8f6f4 v[112:115], v[0:7], v[48:55], v[112:115]
	v_mfma_f32_16x16x128_f8f6f4 v[108:111], v[8:15], v[48:55], v[108:111]
	v_mfma_f32_16x16x128_f8f6f4 v[80:83], v[0:7], v[56:63], v[80:83]
	v_mfma_f32_16x16x128_f8f6f4 v[76:79], v[8:15], v[56:63], v[76:79]
	s_setprio 0
	s_setprio 1
	v_mfma_f32_16x16x128_f8f6f4 v[168:171], v[16:23], v[32:39], v[168:171]
	v_mfma_f32_16x16x128_f8f6f4 v[164:167], v[24:31], v[32:39], v[164:167]
	v_mfma_f32_16x16x128_f8f6f4 v[136:139], v[16:23], v[40:47], v[136:139]
	v_mfma_f32_16x16x128_f8f6f4 v[132:135], v[24:31], v[40:47], v[132:135]
	v_mfma_f32_16x16x128_f8f6f4 v[104:107], v[16:23], v[48:55], v[104:107]
	v_mfma_f32_16x16x128_f8f6f4 v[100:103], v[24:31], v[48:55], v[100:103]
	v_mfma_f32_16x16x128_f8f6f4 v[72:75], v[16:23], v[56:63], v[72:75]
	v_mfma_f32_16x16x128_f8f6f4 v[68:71], v[24:31], v[56:63], v[68:71]
	s_setprio 0
